# SW attention: sink load hoisted above the next-tile Q prefetch, counted vmcnt so the prefetch stays in flight
# speedup vs baseline: 1.0002x; 1.0002x over previous
; __device__ __forceinline__ void sw_attn(const bf16* QKV, const float* rope, const float* qg, const float* kg, const float* sinks, bf16* O, LAS unsigned char* lds, int tid) {
;     ...
;                     for (int ks = 0; ks < 4; ++ks) { const bf16x8 a = *(const LAS bf16x8*)(kl + (32 * (tb + js) + l32) * KROW + 32 * ks + 16 * hi); s[js] = SB_MFMA(a, qf[ks], s[js]); }
; #pragma unroll
;                     for (int r = 0; r < 16; ++r) {
;                         const int kk = (r & 3) + 8 * (r >> 2) + 4 * hi;
;                         float v = s[js][r];
;                         if (js == 0) v = (kk > l32) ? v : NEG;
;                         if (js == 4) v = (kk <= l32) ? v : NEG;
;                         s[js][r] = v; mx = fmaxf(mx, v);
;                     }
;                 } else {
; #pragma unroll
;                     for (int r = 0; r < 16; ++r) s[js][r] = NEG;
;                 }
;                 asm volatile("" ::: "memory");
;             }
;             { float lo_, up_; halves(mx, lo_, up_); mx = fmaxf(lo_, up_); }
;             float l = 0.f;
;             f32x16 o0, o1;
; #pragma unroll
;             for (int r = 0; r < 16; ++r) { o0[r] = 0.f; o1[r] = 0.f; }
; #pragma unroll
;             for (int js = 0; js < 5; ++js) {
;                 unsigned pw[8];
; #pragma unroll
;                 for (int r = 0; r < 16; r += 2) { const float p0 = __builtin_amdgcn_exp2f(s[js][r] - mx), p1 = __builtin_amdgcn_exp2f(s[js][r + 1] - mx); l += p0 + p1; pw[r >> 1] = cvtpk(p0, p1); }
; #pragma unroll
;                 for (int kk = 0; kk < 2; ++kk) {
;                     const v4u pv = {pw[4 * kk], pw[4 * kk + 1], pw[4 * kk + 2], pw[4 * kk + 3]};
;                     const bf16x8 pb = __builtin_bit_cast(bf16x8, pv);
; #pragma unroll
;                     for (int dh = 0; dh < 2; ++dh) {
;                         const LAS unsigned char* vp = vl + (32 * dh + l32) * VROW + (32 * (tb + js) + 16 * kk + 4 * hi) * 2;
;                         const u32x2 lo = *(const LAS u32x2*)vp, hi2 = *(const LAS u32x2*)(vp + 16);
;                         const v4u av = {lo[0], lo[1], hi2[0], hi2[1]};
;                         const bf16x8 a = __builtin_bit_cast(bf16x8, av);
;                         if (dh == 0) o0 = SB_MFMA(a, pb, o0); else o1 = SB_MFMA(a, pb, o1);
;                     }
;                 }
;                 asm volatile("" ::: "memory");
.LBB0_173:
	ds_read_b128 v[22:25], v138
	ds_read_b128 v[146:149], v138 offset:32
	v_add_u32_e32 v195, 0xd000, v139
	s_lshl_b32 s18, s18, 6
	s_ashr_i32 s19, s18, 31
	s_waitcnt lgkmcnt(1)
	v_mfma_f32_32x32x16_bf16 v[16:31], v[22:25], v[18:21], 0
	s_add_i32 s34, s34, 8
	s_cmp_eq_u32 s34, 32
	s_waitcnt lgkmcnt(0)
	v_mfma_f32_32x32x16_bf16 v[16:31], v[146:149], v[36:39], v[16:31]
	ds_read_b128 v[36:39], v138 offset:64
	ds_read_b128 v[146:149], v138 offset:96
	s_waitcnt lgkmcnt(1)
	v_mfma_f32_32x32x16_bf16 v[16:31], v[36:39], v[40:43], v[16:31]
	v_add_u32_e32 v40, 0x9000, v139
	s_waitcnt lgkmcnt(0)
	v_mfma_f32_32x32x16_bf16 v[16:31], v[146:149], v[32:35], v[16:31]
	s_nop 11
	v_cndmask_b32_e64 v172, v16, v234, s[42:43]
	v_cndmask_b32_e64 v171, v234, v17, s[44:45]
	v_cndmask_b32_e64 v170, v18, v234, s[46:47]
	v_cndmask_b32_e64 v169, v19, v234, s[48:49]
	v_max3_f32 v16, v144, v172, v171
	v_cndmask_b32_e64 v158, v20, v234, s[50:51]
	v_cndmask_b32_e64 v155, v21, v234, s[52:53]
	v_max3_f32 v16, v16, v170, v169
	v_cndmask_b32_e64 v154, v22, v234, s[54:55]
	v_cndmask_b32_e64 v153, v23, v234, s[56:57]
	v_max3_f32 v16, v16, v158, v155
	v_cndmask_b32_e64 v152, v24, v234, s[58:59]
	v_cndmask_b32_e64 v151, v25, v234, s[60:61]
	v_max3_f32 v16, v16, v154, v153
	v_cndmask_b32_e64 v150, v26, v234, s[62:63]
	v_cndmask_b32_e64 v149, v27, v234, s[64:65]
	v_max3_f32 v16, v16, v152, v151
	v_cndmask_b32_e64 v148, v28, v234, s[66:67]
	v_cndmask_b32_e64 v147, v29, v234, s[68:69]
	v_max3_f32 v16, v16, v150, v149
	v_cndmask_b32_e64 v146, v30, v234, s[70:71]
	v_cndmask_b32_e64 v145, v31, v234, s[72:73]
	v_max3_f32 v16, v16, v148, v147
	v_max3_f32 v16, v16, v146, v145
	v_mov_b32_e32 v17, v16
	ds_read2_b64 v[36:39], v195 offset0:32 offset1:34
	s_nop 0
	v_permlane32_swap_b32_e32 v16, v17
	v_max_f32_e32 v17, v17, v17
	v_max_f32_e32 v16, v16, v16
	v_max_f32_e32 v144, v16, v17
	v_sub_f32_e32 v16, v182, v144
	v_sub_f32_e32 v17, v183, v144
	v_sub_f32_e32 v18, v178, v144
	v_sub_f32_e32 v19, v179, v144
	v_sub_f32_e32 v22, v156, v144
	v_exp_f32_e32 v183, v16
	v_exp_f32_e32 v185, v17
	v_exp_f32_e32 v182, v18
	v_exp_f32_e32 v156, v19
	ds_read2_b64 v[16:19], v40 offset1:2
	v_sub_f32_e32 v20, v180, v144
	v_sub_f32_e32 v21, v181, v144
	v_sub_f32_e32 v23, v176, v144
	v_exp_f32_e32 v187, v20
	v_exp_f32_e32 v189, v21
	v_exp_f32_e32 v184, v22
	v_exp_f32_e32 v186, v23
	v_sub_f32_e32 v20, v47, v144
	v_sub_f32_e32 v24, v177, v144
	v_cvt_pk_bf16_f32 v32, v183, v185
	v_cvt_pk_bf16_f32 v33, v182, v156
	v_cvt_pk_bf16_f32 v34, v187, v189
	v_cvt_pk_bf16_f32 v35, v184, v186
	v_exp_f32_e32 v193, v20
	v_sub_f32_e32 v20, v174, v144
	v_sub_f32_e32 v41, v175, v144
	ds_read2_b64 v[174:177], v40 offset0:4 offset1:6
	v_exp_f32_e32 v191, v24
	v_exp_f32_e32 v188, v20
	s_waitcnt lgkmcnt(1)
	v_mfma_f32_32x32x16_bf16 v[16:31], v[16:19], v[32:35], 0
	v_exp_f32_e32 v190, v41
	v_sub_f32_e32 v41, v44, v144
	v_exp_f32_e32 v196, v41
	v_sub_f32_e32 v41, v45, v144
	v_sub_f32_e32 v178, v46, v144
	v_sub_f32_e32 v173, v173, v144
	v_exp_f32_e32 v197, v41
	v_exp_f32_e32 v192, v178
	v_exp_f32_e32 v194, v173
	v_cvt_pk_bf16_f32 v178, v191, v193
	v_cvt_pk_bf16_f32 v179, v188, v190
	v_cvt_pk_bf16_f32 v180, v196, v197
	v_cvt_pk_bf16_f32 v181, v192, v194
	v_mfma_f32_32x32x16_bf16 v[32:47], v[36:39], v[32:35], 0
	v_add_f32_e32 v183, v183, v185
	v_add_f32_e32 v185, v187, v189
	v_add_f32_e32 v189, v191, v193
	v_sub_f32_e32 v0, v0, v144
	v_add_f32_e32 v193, v196, v197
	v_sub_f32_e32 v8, v8, v144
	v_sub_f32_e32 v14, v14, v144
	s_waitcnt lgkmcnt(0)
	v_mfma_f32_32x32x16_bf16 v[16:31], v[174:177], v[178:181], v[16:31]
	ds_read2_b64 v[174:177], v195 offset0:36 offset1:38
	s_waitcnt lgkmcnt(0)
	v_mfma_f32_32x32x16_bf16 v[32:47], v[174:177], v[178:181], v[32:47]
	v_add_f32_e64 v174, v182, v156
	v_add_f32_e64 v175, v183, v157
	v_exp_f32_e32 v156, v0
	v_pk_add_f32 v[174:175], v[174:175], v[174:175] op_sel_hi:[0,1]
	v_mov_b32_e32 v187, v175
	v_pk_add_f32 v[174:175], v[184:185], v[186:187]
	v_sub_f32_e32 v0, v1, v144
	v_pk_add_f32 v[174:175], v[174:175], v[174:175] op_sel_hi:[0,1]
	v_mov_b32_e32 v191, v175
	v_pk_add_f32 v[174:175], v[188:189], v[190:191]
	v_exp_f32_e32 v173, v0
	v_pk_add_f32 v[174:175], v[174:175], v[174:175] op_sel_hi:[0,1]
	v_mov_b32_e32 v195, v175
	v_pk_add_f32 v[174:175], v[192:193], v[194:195]
	v_sub_f32_e32 v0, v2, v144
	v_pk_add_f32 v[174:175], v[174:175], v[174:175] op_sel_hi:[0,1]
	v_exp_f32_e32 v176, v0
	v_sub_f32_e32 v0, v3, v144
	v_exp_f32_e32 v174, v0
	v_sub_f32_e32 v0, v4, v144
	v_exp_f32_e32 v179, v0
	v_sub_f32_e32 v0, v5, v144
	v_exp_f32_e32 v181, v0
	v_sub_f32_e32 v0, v6, v144
	v_add_u32_e32 v177, 0x9000, v140
	v_exp_f32_e32 v178, v0
	v_sub_f32_e32 v0, v7, v144
	ds_read2_b64 v[4:7], v177 offset1:2
	v_exp_f32_e32 v183, v8
	v_sub_f32_e32 v8, v9, v144
	v_exp_f32_e32 v180, v0
	v_exp_f32_e32 v185, v8
	v_sub_f32_e32 v8, v10, v144
	v_add_u32_e32 v186, 0xd000, v140
	v_exp_f32_e32 v182, v8
	v_sub_f32_e32 v184, v11, v144
	ds_read2_b64 v[8:11], v186 offset0:32 offset1:34
	v_cvt_pk_bf16_f32 v0, v156, v173
	v_cvt_pk_bf16_f32 v1, v176, v174
	v_cvt_pk_bf16_f32 v2, v179, v181
	v_cvt_pk_bf16_f32 v3, v178, v180
	v_exp_f32_e32 v184, v184
	v_add_f32_e32 v179, v179, v181
	s_waitcnt lgkmcnt(1)
	v_mfma_f32_32x32x16_bf16 v[16:31], v[4:7], v[0:3], v[16:31]
	v_sub_f32_e32 v4, v12, v144
	v_exp_f32_e32 v12, v4
	v_sub_f32_e32 v4, v13, v144
	v_exp_f32_e32 v13, v4
	ds_read2_b64 v[4:7], v177 offset0:4 offset1:6
	v_add_f32_e32 v177, v156, v173
	s_waitcnt lgkmcnt(1)
	v_mfma_f32_32x32x16_bf16 v[32:47], v[8:11], v[0:3], v[32:47]
	v_sub_f32_e32 v0, v15, v144
	v_exp_f32_e32 v8, v14
	v_exp_f32_e32 v10, v0
	v_cvt_pk_bf16_f32 v0, v183, v185
	v_cvt_pk_bf16_f32 v1, v182, v184
	v_cvt_pk_bf16_f32 v2, v12, v13
	v_cvt_pk_bf16_f32 v3, v8, v10
	v_add_f32_e32 v183, v183, v185
	v_add_f32_e32 v9, v12, v13
	s_waitcnt lgkmcnt(0)
; #define LAS __attribute__((address_space(3)))
; __device__ __forceinline__ unsigned cvtpk(float lo, float hi) { f32x2_t v = {lo, hi}; bf16x2_t b = __builtin_convertvector(v, bf16x2_t); return __builtin_bit_cast(unsigned, b); }
; #define SB_MFMA(a, b, c) __builtin_amdgcn_mfma_f32_32x32x16_bf16((a), (b), (c), 0, 0, 0)
; __device__ __forceinline__ void sw_attn(const bf16* QKV, const float* rope, const float* qg, const float* kg, const float* sinks, bf16* O, LAS unsigned char* lds, int tid) {
;     ...
;             for (int js = 0; js < 5; ++js) {
;                 unsigned pw[8];
; #pragma unroll
;                 for (int r = 0; r < 16; r += 2) { const float p0 = __builtin_amdgcn_exp2f(s[js][r] - mx), p1 = __builtin_amdgcn_exp2f(s[js][r + 1] - mx); l += p0 + p1; pw[r >> 1] = cvtpk(p0, p1); }
; #pragma unroll
;                 for (int kk = 0; kk < 2; ++kk) {
;                     const v4u pv = {pw[4 * kk], pw[4 * kk + 1], pw[4 * kk + 2], pw[4 * kk + 3]};
;                     const bf16x8 pb = __builtin_bit_cast(bf16x8, pv);
; #pragma unroll
;                     for (int dh = 0; dh < 2; ++dh) {
;                         const LAS unsigned char* vp = vl + (32 * dh + l32) * VROW + (32 * (tb + js) + 16 * kk + 4 * hi) * 2;
;                         const u32x2 lo = *(const LAS u32x2*)vp, hi2 = *(const LAS u32x2*)(vp + 16);
;                         const v4u av = {lo[0], lo[1], hi2[0], hi2[1]};
;                         const bf16x8 a = __builtin_bit_cast(bf16x8, av);
;                         if (dh == 0) o0 = SB_MFMA(a, pb, o0); else o1 = SB_MFMA(a, pb, o1);
;                     }
;                 }
;                 asm volatile("" ::: "memory");
	v_mfma_f32_32x32x16_bf16 v[16:31], v[4:7], v[0:3], v[16:31]
	ds_read2_b64 v[4:7], v186 offset0:36 offset1:38
	s_waitcnt lgkmcnt(0)
	v_mfma_f32_32x32x16_bf16 v[32:47], v[4:7], v[0:3], v[32:47]
	v_add_f32_e64 v0, v176, v174
	v_add_f32_e64 v1, v177, v175
	v_pk_add_f32 v[0:1], v[0:1], v[0:1] op_sel_hi:[0,1]
	v_mov_b32_e32 v181, v1
	v_pk_add_f32 v[0:1], v[178:179], v[180:181]
	s_nop 0
	v_pk_add_f32 v[0:1], v[0:1], v[0:1] op_sel_hi:[0,1]
	v_mov_b32_e32 v185, v1
	v_pk_add_f32 v[0:1], v[182:183], v[184:185]
	s_nop 0
	v_pk_add_f32 v[0:1], v[0:1], v[0:1] op_sel_hi:[0,1]
	v_mov_b32_e32 v11, v1
	v_pk_add_f32 v[0:1], v[8:9], v[10:11]
	v_sub_f32_e32 v8, v72, v144
	v_pk_add_f32 v[12:13], v[0:1], v[0:1] op_sel_hi:[0,1]
	v_sub_f32_e32 v0, v64, v144
	v_exp_f32_e32 v15, v0
	v_sub_f32_e32 v0, v65, v144
	v_exp_f32_e32 v65, v0
	v_sub_f32_e32 v0, v66, v144
	v_exp_f32_e32 v14, v0
	v_sub_f32_e32 v0, v67, v144
	v_exp_f32_e32 v12, v0
	v_sub_f32_e32 v0, v68, v144
	v_exp_f32_e32 v67, v0
	v_sub_f32_e32 v0, v69, v144
	v_exp_f32_e32 v69, v0
	v_sub_f32_e32 v0, v70, v144
	v_exp_f32_e32 v64, v0
	v_sub_f32_e32 v0, v71, v144
	v_add_u32_e32 v71, 0x9000, v141
	ds_read2_b64 v[4:7], v71 offset1:2
	v_exp_f32_e32 v72, v8
	v_sub_f32_e32 v8, v73, v144
	v_exp_f32_e32 v66, v0
	v_exp_f32_e32 v73, v8
	v_sub_f32_e32 v8, v74, v144
	v_add_u32_e32 v74, 0xd000, v141
	v_exp_f32_e32 v68, v8
	ds_read2_b64 v[8:11], v74 offset0:32 offset1:34
	v_cvt_pk_bf16_f32 v0, v15, v65
	v_cvt_pk_bf16_f32 v1, v14, v12
	v_cvt_pk_bf16_f32 v2, v67, v69
	v_cvt_pk_bf16_f32 v3, v64, v66
	v_sub_f32_e32 v70, v75, v144
	v_exp_f32_e32 v70, v70
	s_waitcnt lgkmcnt(1)
	v_mfma_f32_32x32x16_bf16 v[16:31], v[4:7], v[0:3], v[16:31]
	v_sub_f32_e32 v4, v76, v144
	v_exp_f32_e32 v75, v4
	v_sub_f32_e32 v4, v77, v144
	v_exp_f32_e32 v76, v4
	ds_read2_b64 v[4:7], v71 offset0:4 offset1:6
	v_sub_f32_e32 v77, v78, v144
	v_add_f32_e32 v15, v15, v65
	s_waitcnt lgkmcnt(1)
	v_mfma_f32_32x32x16_bf16 v[32:47], v[8:11], v[0:3], v[32:47]
	v_sub_f32_e32 v0, v79, v144
	v_exp_f32_e32 v8, v77
	v_exp_f32_e32 v10, v0
	v_cvt_pk_bf16_f32 v0, v72, v73
	v_cvt_pk_bf16_f32 v1, v68, v70
	v_cvt_pk_bf16_f32 v2, v75, v76
	v_cvt_pk_bf16_f32 v3, v8, v10
	v_add_f32_e32 v65, v67, v69
	v_add_f32_e32 v69, v72, v73
	s_waitcnt lgkmcnt(0)
	v_mfma_f32_32x32x16_bf16 v[16:31], v[4:7], v[0:3], v[16:31]
	ds_read2_b64 v[4:7], v74 offset0:36 offset1:38
	v_add_f32_e32 v9, v75, v76
	s_waitcnt lgkmcnt(0)
	v_mfma_f32_32x32x16_bf16 v[32:47], v[4:7], v[0:3], v[32:47]
	v_add_f32_e64 v0, v14, v12
	v_add_f32_e64 v1, v15, v13
	v_pk_add_f32 v[0:1], v[0:1], v[0:1] op_sel_hi:[0,1]
	v_mov_b32_e32 v67, v1
	v_pk_add_f32 v[0:1], v[64:65], v[66:67]
	s_nop 0
	v_pk_add_f32 v[0:1], v[0:1], v[0:1] op_sel_hi:[0,1]
	v_mov_b32_e32 v71, v1
	v_pk_add_f32 v[0:1], v[68:69], v[70:71]
	s_nop 0
	v_pk_add_f32 v[0:1], v[0:1], v[0:1] op_sel_hi:[0,1]
	v_mov_b32_e32 v11, v1
	v_pk_add_f32 v[0:1], v[8:9], v[10:11]
	v_sub_f32_e32 v8, v56, v144
	v_pk_add_f32 v[12:13], v[0:1], v[0:1] op_sel_hi:[0,1]
	v_sub_f32_e32 v0, v48, v144
	v_exp_f32_e32 v15, v0
	v_sub_f32_e32 v0, v49, v144
	v_exp_f32_e32 v49, v0
	v_sub_f32_e32 v0, v50, v144
	v_exp_f32_e32 v14, v0
	v_sub_f32_e32 v0, v51, v144
	v_exp_f32_e32 v12, v0
	v_sub_f32_e32 v0, v52, v144
	v_exp_f32_e32 v51, v0
	v_sub_f32_e32 v0, v53, v144
	v_exp_f32_e32 v53, v0
	v_sub_f32_e32 v0, v54, v144
	v_exp_f32_e32 v48, v0
	v_sub_f32_e32 v0, v55, v144
	v_add_u32_e32 v55, 0x9000, v142
	ds_read2_b64 v[4:7], v55 offset1:2
	v_exp_f32_e32 v56, v8
	v_sub_f32_e32 v8, v57, v144
	v_exp_f32_e32 v50, v0
	v_exp_f32_e32 v57, v8
	v_sub_f32_e32 v8, v58, v144
	v_add_u32_e32 v58, 0xd000, v142
	v_exp_f32_e32 v52, v8
	ds_read2_b64 v[8:11], v58 offset0:32 offset1:34
	v_cvt_pk_bf16_f32 v0, v15, v49
	v_cvt_pk_bf16_f32 v1, v14, v12
	v_cvt_pk_bf16_f32 v2, v51, v53
	v_cvt_pk_bf16_f32 v3, v48, v50
	v_sub_f32_e32 v54, v59, v144
	v_exp_f32_e32 v54, v54
	s_waitcnt lgkmcnt(1)
	v_mfma_f32_32x32x16_bf16 v[16:31], v[4:7], v[0:3], v[16:31]
	v_sub_f32_e32 v4, v60, v144
	v_exp_f32_e32 v59, v4
	v_sub_f32_e32 v4, v61, v144
	v_exp_f32_e32 v60, v4
	ds_read2_b64 v[4:7], v55 offset0:4 offset1:6
	v_sub_f32_e32 v61, v62, v144
	v_add_f32_e32 v15, v15, v49
	s_waitcnt lgkmcnt(1)
	v_mfma_f32_32x32x16_bf16 v[32:47], v[8:11], v[0:3], v[32:47]
	v_sub_f32_e32 v0, v63, v144
	v_exp_f32_e32 v8, v61
	v_exp_f32_e32 v10, v0
	v_cvt_pk_bf16_f32 v0, v56, v57
	v_cvt_pk_bf16_f32 v1, v52, v54
	v_cvt_pk_bf16_f32 v2, v59, v60
	v_cvt_pk_bf16_f32 v3, v8, v10
	v_add_f32_e32 v49, v51, v53
	v_add_f32_e32 v53, v56, v57
	s_waitcnt lgkmcnt(0)
	v_mfma_f32_32x32x16_bf16 v[16:31], v[4:7], v[0:3], v[16:31]
	ds_read2_b64 v[4:7], v58 offset0:36 offset1:38
	v_add_f32_e32 v9, v59, v60
	v_add_u32_e32 v57, 0xd000, v143
	s_waitcnt lgkmcnt(0)
	v_mfma_f32_32x32x16_bf16 v[32:47], v[4:7], v[0:3], v[32:47]
	v_add_f32_e64 v0, v14, v12
	v_add_f32_e64 v1, v15, v13
	v_sub_f32_e32 v2, v170, v144
	v_pk_add_f32 v[0:1], v[0:1], v[0:1] op_sel_hi:[0,1]
	v_mov_b32_e32 v51, v1
	v_pk_add_f32 v[0:1], v[48:49], v[50:51]
	v_exp_f32_e32 v48, v2
	v_pk_add_f32 v[0:1], v[0:1], v[0:1] op_sel_hi:[0,1]
	v_mov_b32_e32 v55, v1
	v_pk_add_f32 v[0:1], v[52:53], v[54:55]
	v_sub_f32_e32 v2, v169, v144
	v_pk_add_f32 v[0:1], v[0:1], v[0:1] op_sel_hi:[0,1]
	v_mov_b32_e32 v11, v1
	v_pk_add_f32 v[0:1], v[8:9], v[10:11]
	v_sub_f32_e32 v3, v155, v144
	v_pk_add_f32 v[14:15], v[0:1], v[0:1] op_sel_hi:[0,1]
	v_exp_f32_e32 v14, v2
	v_sub_f32_e32 v2, v158, v144
	v_exp_f32_e32 v2, v2
	v_exp_f32_e32 v3, v3
	v_add_u32_e32 v53, 0x9000, v143
	ds_read2_b64 v[4:7], v53 offset1:2
	v_sub_f32_e32 v0, v172, v144
	v_add_f32_e32 v51, v2, v3
	v_cvt_pk_bf16_f32 v2, v2, v3
	v_sub_f32_e32 v3, v154, v144
	v_sub_f32_e32 v1, v171, v144
	v_exp_f32_e32 v50, v3
	v_sub_f32_e32 v3, v153, v144
	v_exp_f32_e32 v0, v0
	v_exp_f32_e32 v1, v1
	v_exp_f32_e32 v52, v3
	ds_read2_b64 v[10:13], v57 offset0:32 offset1:34
	v_sub_f32_e32 v3, v152, v144
	v_exp_f32_e32 v8, v3
	v_sub_f32_e32 v3, v151, v144
	v_add_f32_e32 v49, v0, v1
	v_cvt_pk_bf16_f32 v0, v0, v1
	v_cvt_pk_bf16_f32 v1, v48, v14
	v_exp_f32_e32 v9, v3
	v_cvt_pk_bf16_f32 v3, v50, v52
	v_add_f32_e32 v55, v8, v9
	s_waitcnt lgkmcnt(1)
; #define LAS __attribute__((address_space(3)))
; __device__ __forceinline__ unsigned cvtpk(float lo, float hi) { f32x2_t v = {lo, hi}; bf16x2_t b = __builtin_convertvector(v, bf16x2_t); return __builtin_bit_cast(unsigned, b); }
; #define SB_MFMA(a, b, c) __builtin_amdgcn_mfma_f32_32x32x16_bf16((a), (b), (c), 0, 0, 0)
; __device__ __forceinline__ void sw_attn(const bf16* QKV, const float* rope, const float* qg, const float* kg, const float* sinks, bf16* O, LAS unsigned char* lds, int tid) {
;     ...
;                 for (int r = 0; r < 16; r += 2) { const float p0 = __builtin_amdgcn_exp2f(s[js][r] - mx), p1 = __builtin_amdgcn_exp2f(s[js][r + 1] - mx); l += p0 + p1; pw[r >> 1] = cvtpk(p0, p1); }
; #pragma unroll
;                 for (int kk = 0; kk < 2; ++kk) {
;                     const v4u pv = {pw[4 * kk], pw[4 * kk + 1], pw[4 * kk + 2], pw[4 * kk + 3]};
;                     const bf16x8 pb = __builtin_bit_cast(bf16x8, pv);
; #pragma unroll
;                     for (int dh = 0; dh < 2; ++dh) {
;                         const LAS unsigned char* vp = vl + (32 * dh + l32) * VROW + (32 * (tb + js) + 16 * kk + 4 * hi) * 2;
;                         const u32x2 lo = *(const LAS u32x2*)vp, hi2 = *(const LAS u32x2*)(vp + 16);
;                         const v4u av = {lo[0], lo[1], hi2[0], hi2[1]};
;                         const bf16x8 a = __builtin_bit_cast(bf16x8, av);
;                         if (dh == 0) o0 = SB_MFMA(a, pb, o0); else o1 = SB_MFMA(a, pb, o1);
;                     }
;                 }
;                 asm volatile("" ::: "memory");
;             }
;             { float lo_, up_; halves(l, lo_, up_); l = lo_ + up_; }
;             l += __builtin_amdgcn_exp2f(sink - mx);
;             const float il = 1.0f / l;
;             bf16* op = O + qrow * D + hq * 64 + 4 * hi;
; #pragma unroll
;             for (int gg = 0; gg < 4; ++gg) {
;                 const u32x2 a = {cvtpk(o0[4 * gg] * il, o0[4 * gg + 1] * il), cvtpk(o0[4 * gg + 2] * il, o0[4 * gg + 3] * il)}, c = {cvtpk(o1[4 * gg] * il, o1[4 * gg + 1] * il), cvtpk(o1[4 * gg + 2] * il, o1[4 * gg + 3] * il)};
;                 *(u32x2*)(op + 8 * gg) = a; *(u32x2*)(op + 32 + 8 * gg) = c; }
	v_mfma_f32_32x32x16_bf16 v[16:31], v[4:7], v[0:3], v[16:31]
	v_sub_f32_e32 v4, v148, v144
	v_exp_f32_e32 v59, v4
	v_sub_f32_e32 v4, v147, v144
	v_exp_f32_e32 v60, v4
	ds_read2_b64 v[4:7], v53 offset0:4 offset1:6
	v_cvt_pk_bf16_f32 v8, v8, v9
	v_sub_f32_e32 v9, v150, v144
	v_exp_f32_e32 v54, v9
	v_sub_f32_e32 v9, v149, v144
	v_exp_f32_e32 v56, v9
	v_sub_f32_e32 v9, v146, v144
	s_waitcnt lgkmcnt(1)
	v_mfma_f32_32x32x16_bf16 v[32:47], v[10:13], v[0:3], v[32:47]
	v_sub_f32_e32 v0, v145, v144
	v_exp_f32_e32 v12, v9
	v_exp_f32_e32 v58, v0
	v_cvt_pk_bf16_f32 v9, v54, v56
	v_cvt_pk_bf16_f32 v10, v59, v60
	ds_read2_b64 v[0:3], v57 offset0:36 offset1:38
	v_cvt_pk_bf16_f32 v11, v12, v58
	v_add_f32_e32 v13, v59, v60
	s_waitcnt lgkmcnt(1)
	v_mfma_f32_32x32x16_bf16 v[16:31], v[4:7], v[8:11], v[16:31]
	v_add_f32_e64 v4, v48, v14
	v_add_f32_e64 v5, v49, v15
	v_sub_f32_e32 v6, v123, v144
	v_pk_add_f32 v[4:5], v[4:5], v[4:5] op_sel_hi:[0,1]
	v_mov_b32_e32 v53, v5
	v_pk_add_f32 v[4:5], v[50:51], v[52:53]
	v_exp_f32_e32 v6, v6
	v_pk_add_f32 v[4:5], v[4:5], v[4:5] op_sel_hi:[0,1]
	v_mov_b32_e32 v57, v5
	v_pk_add_f32 v[4:5], v[54:55], v[56:57]
	s_waitcnt lgkmcnt(0)
	v_mfma_f32_32x32x16_bf16 v[32:47], v[0:3], v[8:11], v[32:47]
	v_pk_add_f32 v[4:5], v[4:5], v[4:5] op_sel_hi:[0,1]
	v_mov_b32_e32 v59, v5
	v_pk_add_f32 v[4:5], v[12:13], v[58:59]
	s_waitcnt vmcnt(0)
	v_mov_b64_e32 v[12:13], v[108:109]
	v_pk_add_f32 v[4:5], v[4:5], v[4:5] op_sel:[0,1] op_sel_hi:[1,0]
	v_mov_b64_e32 v[14:15], v[110:111]
	v_mov_b32_e32 v5, v4
	s_nop 1
	v_permlane32_swap_b32_e32 v4, v5
	v_add_f32_e32 v4, v4, v5
	v_add_f32_e32 v4, v6, v4
	v_div_scale_f32 v5, s[20:21], v4, v4, 1.0
	v_rcp_f32_e32 v6, v5
	s_nop 0
	v_fma_f32 v0, -v5, v6, 1.0
	v_fmac_f32_e32 v6, v0, v6
	v_div_scale_f32 v0, vcc, 1.0, v4, 1.0
	v_mul_f32_e32 v1, v0, v6
	v_fma_f32 v2, -v5, v1, v0
	v_fmac_f32_e32 v1, v2, v6
	v_fma_f32 v0, -v5, v1, v0
	v_div_fmas_f32 v0, v0, v6, v1
	v_div_fixup_f32 v0, v0, v4, 1.0
	v_pk_mul_f32 v[4:5], v[16:17], v[0:1] op_sel_hi:[1,0]
	v_pk_mul_f32 v[6:7], v[18:19], v[0:1] op_sel_hi:[1,0]
	v_cvt_pk_bf16_f32 v4, v4, v5
	v_cvt_pk_bf16_f32 v5, v6, v7
	v_pk_mul_f32 v[6:7], v[32:33], v[0:1] op_sel_hi:[1,0]
	v_pk_mul_f32 v[8:9], v[34:35], v[0:1] op_sel_hi:[1,0]
	v_lshl_add_u64 v[2:3], s[18:19], 1, v[126:127]
	v_cvt_pk_bf16_f32 v6, v6, v7
	v_cvt_pk_bf16_f32 v7, v8, v9
	global_store_dwordx2 v[2:3], v[4:5], off
	global_store_dwordx2 v[2:3], v[6:7], off offset:64
	v_pk_mul_f32 v[4:5], v[20:21], v[0:1] op_sel_hi:[1,0]
	v_pk_mul_f32 v[6:7], v[22:23], v[0:1] op_sel_hi:[1,0]
	v_cvt_pk_bf16_f32 v4, v4, v5
	v_cvt_pk_bf16_f32 v5, v6, v7
	v_pk_mul_f32 v[6:7], v[36:37], v[0:1] op_sel_hi:[1,0]
	v_pk_mul_f32 v[8:9], v[38:39], v[0:1] op_sel_hi:[1,0]
	v_cvt_pk_bf16_f32 v6, v6, v7
	v_cvt_pk_bf16_f32 v7, v8, v9
	global_store_dwordx2 v[2:3], v[4:5], off offset:16
	global_store_dwordx2 v[2:3], v[6:7], off offset:80
	v_pk_mul_f32 v[4:5], v[24:25], v[0:1] op_sel_hi:[1,0]
	v_pk_mul_f32 v[6:7], v[26:27], v[0:1] op_sel_hi:[1,0]
	v_cvt_pk_bf16_f32 v4, v4, v5
	v_cvt_pk_bf16_f32 v5, v6, v7
	v_pk_mul_f32 v[6:7], v[40:41], v[0:1] op_sel_hi:[1,0]
	v_pk_mul_f32 v[8:9], v[42:43], v[0:1] op_sel_hi:[1,0]
	v_cvt_pk_bf16_f32 v6, v6, v7
	v_cvt_pk_bf16_f32 v7, v8, v9
	global_store_dwordx2 v[2:3], v[4:5], off offset:32
	global_store_dwordx2 v[2:3], v[6:7], off offset:96
	v_pk_mul_f32 v[4:5], v[28:29], v[0:1] op_sel_hi:[1,0]
	v_pk_mul_f32 v[6:7], v[30:31], v[0:1] op_sel_hi:[1,0]
	v_cvt_pk_bf16_f32 v4, v4, v5
	v_cvt_pk_bf16_f32 v5, v6, v7
	v_pk_mul_f32 v[6:7], v[44:45], v[0:1] op_sel_hi:[1,0]
	v_pk_mul_f32 v[0:1], v[46:47], v[0:1] op_sel_hi:[1,0]
	v_cvt_pk_bf16_f32 v6, v6, v7
	v_cvt_pk_bf16_f32 v7, v0, v1
	global_store_dwordx2 v[2:3], v[4:5], off offset:48
	global_store_dwordx2 v[2:3], v[6:7], off offset:112
	v_mov_b64_e32 v[4:5], v[96:97]
	v_mov_b64_e32 v[0:1], v[100:101]
	v_mov_b64_e32 v[8:9], v[104:105]
	v_mov_b64_e32 v[6:7], v[98:99]
	v_mov_b64_e32 v[2:3], v[102:103]
	v_mov_b64_e32 v[10:11], v[106:107]
	s_cbranch_scc1 .LBB0_158
; #define LAS __attribute__((address_space(3)))
; __device__ __forceinline__ unsigned cvtpk(float lo, float hi) { f32x2_t v = {lo, hi}; bf16x2_t b = __builtin_convertvector(v, bf16x2_t); return __builtin_bit_cast(unsigned, b); }
; __device__ __forceinline__ void unpack8(const v4u w, float* v) { v[0] = bf_lo(w.x); v[1] = bf_hi(w.x); v[2] = bf_lo(w.y); v[3] = bf_hi(w.y); v[4] = bf_lo(w.z); v[5] = bf_hi(w.z); v[6] = bf_lo(w.w); v[7] = bf_hi(w.w); }
; __device__ __forceinline__ void sw_attn(const bf16* QKV, const float* rope, const float* qg, const float* kg, const float* sinks, bf16* O, LAS unsigned char* lds, int tid) {
;     ...
;             {
;                 float qv[4][8]; float ss = 0.f;
; #pragma unroll
;                 for (int ks = 0; ks < 4; ++ks) { unpack8(qraw[ks], qv[ks]);
; #pragma unroll
;                     for (int i = 0; i < 8; ++i) ss = fmaf(qv[ks][i], qv[ks][i], ss); }
;                 { float lo_, up_; halves(ss, lo_, up_); ss = lo_ + up_; }
;                 const float rs = __builtin_amdgcn_rsqf(ss * (1.0f / 64.0f) + 1e-6f);
; #pragma unroll
;                 for (int ks = 0; ks < 4; ++ks) { const f32x4 g0 = *(const LAS f32x4*)(gtab + 16 * ks + 8 * hi), g1 = *(const LAS f32x4*)(gtab + 16 * ks + 8 * hi + 4);
; #pragma unroll
;                     for (int i = 0; i < 8; ++i) qv[ks][i] = qv[ks][i] * rs * (i < 4 ? g0[i & 3] : g1[i & 3]); }
; #pragma unroll
;                 for (int i = 0; i < 8; ++i) { float lo_, up_; const float own = qv[0][i]; halves(own, lo_, up_); const float oth = hi ? lo_ : up_, c = i < 4 ? rraw[0][i & 3] : rraw[1][i & 3], sn = i < 4 ? rraw[2][i & 3] : rraw[3][i & 3]; qv[0][i] = own * c + oth * (hi ? sn : -sn); }
; #pragma unroll
;                 for (int ks = 0; ks < 4; ++ks) { const v4u w = {cvtpk(qv[ks][0] * QS, qv[ks][1] * QS), cvtpk(qv[ks][2] * QS, qv[ks][3] * QS), cvtpk(qv[ks][4] * QS, qv[ks][5] * QS), cvtpk(qv[ks][6] * QS, qv[ks][7] * QS)}; qf[ks] = __builtin_bit_cast(bf16x8, w); }
;             }
;             if (p < 3) SW_LOADQ(p + 1);
;             const float sink = sinks[hq] * 1.4426950408889634f;
.LBB0_174:
	v_lshlrev_b32_e32 v30, 16, v80
	v_and_b32_e32 v31, 0xffff0000, v80
	v_fma_f32 v16, v30, v30, 0
	v_lshlrev_b32_e32 v28, 16, v81
	v_fmac_f32_e32 v16, v31, v31
	v_and_b32_e32 v29, 0xffff0000, v81
	v_fmac_f32_e32 v16, v28, v28
	v_lshlrev_b32_e32 v26, 16, v82
	v_fmac_f32_e32 v16, v29, v29
	v_and_b32_e32 v27, 0xffff0000, v82
	v_fmac_f32_e32 v16, v26, v26
	v_lshlrev_b32_e32 v24, 16, v83
	v_fmac_f32_e32 v16, v27, v27
	v_and_b32_e32 v25, 0xffff0000, v83
	v_fmac_f32_e32 v16, v24, v24
	v_lshlrev_b32_e32 v62, 16, v84
	v_fmac_f32_e32 v16, v25, v25
	v_and_b32_e32 v63, 0xffff0000, v84
	v_fmac_f32_e32 v16, v62, v62
	v_lshlrev_b32_e32 v60, 16, v85
	v_fmac_f32_e32 v16, v63, v63
	v_and_b32_e32 v61, 0xffff0000, v85
	v_fmac_f32_e32 v16, v60, v60
	v_lshlrev_b32_e32 v58, 16, v86
	v_fmac_f32_e32 v16, v61, v61
	v_and_b32_e32 v59, 0xffff0000, v86
	v_fmac_f32_e32 v16, v58, v58
	v_lshlrev_b32_e32 v56, 16, v87
	v_fmac_f32_e32 v16, v59, v59
	v_and_b32_e32 v57, 0xffff0000, v87
	v_fmac_f32_e32 v16, v56, v56
	v_lshlrev_b32_e32 v54, 16, v88
	v_fmac_f32_e32 v16, v57, v57
	v_and_b32_e32 v55, 0xffff0000, v88
	v_fmac_f32_e32 v16, v54, v54
	v_lshlrev_b32_e32 v52, 16, v89
	v_fmac_f32_e32 v16, v55, v55
	v_and_b32_e32 v53, 0xffff0000, v89
	v_fmac_f32_e32 v16, v52, v52
	v_lshlrev_b32_e32 v50, 16, v90
	v_fmac_f32_e32 v16, v53, v53
	v_and_b32_e32 v51, 0xffff0000, v90
	v_fmac_f32_e32 v16, v50, v50
	v_lshlrev_b32_e32 v48, 16, v91
	v_fmac_f32_e32 v16, v51, v51
	v_and_b32_e32 v49, 0xffff0000, v91
	v_fmac_f32_e32 v16, v48, v48
	v_lshlrev_b32_e32 v46, 16, v92
	v_fmac_f32_e32 v16, v49, v49
	v_and_b32_e32 v47, 0xffff0000, v92
	v_fmac_f32_e32 v16, v46, v46
	v_lshlrev_b32_e32 v44, 16, v93
	v_fmac_f32_e32 v16, v47, v47
	v_and_b32_e32 v45, 0xffff0000, v93
	v_fmac_f32_e32 v16, v44, v44
	v_lshlrev_b32_e32 v42, 16, v94
	v_fmac_f32_e32 v16, v45, v45
	v_and_b32_e32 v43, 0xffff0000, v94
	v_fmac_f32_e32 v16, v42, v42
	v_lshlrev_b32_e32 v40, 16, v95
	v_fmac_f32_e32 v16, v43, v43
	v_and_b32_e32 v41, 0xffff0000, v95
	v_fmac_f32_e32 v16, v40, v40
	v_fmac_f32_e32 v16, v41, v41
	v_mov_b32_e32 v17, v16
	ds_read_b128 v[20:23], v131 offset:16
	s_nop 0
	v_permlane32_swap_b32_e32 v16, v17
	v_add_f32_e32 v16, v16, v17
	v_fmamk_f32 v16, v16, 0x3c800000, v232
	v_rsq_f32_e32 v68, v16
	ds_read_b128 v[16:19], v131
	s_add_i32 s18, s99, s34
	s_ashr_i32 s100, s18, 2
	s_add_i32 s100, s100, s30
	s_ashr_i32 s101, s100, 31
	s_lshl_b64 s[100:101], s[100:101], 2
	s_add_u32 s100, s27, s100
	s_addc_u32 s101, s88, s101
	global_load_dword v236, v157, s[100:101]
	s_cmp_eq_u32 s34, 24
	v_pk_mul_f32 v[30:31], v[68:69], v[30:31] op_sel_hi:[0,1]
	s_waitcnt lgkmcnt(0)
	v_pk_mul_f32 v[70:71], v[16:17], v[30:31]
	v_pk_mul_f32 v[16:17], v[68:69], v[28:29] op_sel_hi:[0,1]
	v_pk_mul_f32 v[72:73], v[18:19], v[16:17]
	v_pk_mul_f32 v[16:17], v[68:69], v[26:27] op_sel_hi:[0,1]
	v_pk_mul_f32 v[64:65], v[20:21], v[16:17]
	v_pk_mul_f32 v[16:17], v[68:69], v[24:25] op_sel_hi:[0,1]
	v_pk_mul_f32 v[66:67], v[22:23], v[16:17]
	ds_read_b128 v[36:39], v131 offset:64
	ds_read_b128 v[32:35], v131 offset:80
	ds_read_b128 v[28:31], v131 offset:128
	ds_read_b128 v[24:27], v131 offset:144
	ds_read_b128 v[20:23], v131 offset:192
	ds_read_b128 v[16:19], v131 offset:208
	v_mov_b32_e32 v74, v70
	v_mov_b32_e32 v76, v71
	v_mov_b32_e32 v77, v72
	v_mov_b32_e32 v123, v73
	v_mov_b32_e32 v144, v64
	v_mov_b32_e32 v147, v65
	v_mov_b32_e32 v148, v66
	v_mov_b32_e32 v151, v67
	v_mov_b32_e32 v75, v70
	v_mov_b32_e32 v78, v71
	v_mov_b32_e32 v79, v72
	v_mov_b32_e32 v145, v73
	v_mov_b32_e32 v146, v64
	v_mov_b32_e32 v149, v65
	v_mov_b32_e32 v150, v66
	v_mov_b32_e32 v152, v67
	v_permlane32_swap_b32_e32 v75, v74
	v_permlane32_swap_b32_e32 v78, v76
	v_permlane32_swap_b32_e32 v79, v77
	v_permlane32_swap_b32_e32 v145, v123
	v_permlane32_swap_b32_e32 v146, v144
	v_permlane32_swap_b32_e32 v149, v147
	v_permlane32_swap_b32_e32 v150, v148
	v_permlane32_swap_b32_e32 v152, v151
	s_cbranch_scc1 .Lsw_noprefetch
	s_add_i32 s19, s18, 8
	s_ashr_i32 s19, s19, 2
	s_add_i32 s20, s19, s31
	s_ashr_i32 s21, s20, 31
	s_lshl_b64 s[20:21], s[20:21], 19
	v_lshl_or_b32 v80, v128, 7, s20
	v_mov_b32_e32 v81, s21
	v_lshl_add_u64 v[92:93], v[112:113], 0, v[80:81]
	global_load_dwordx4 v[108:111], v[124:125], off offset:48
	global_load_dwordx4 v[104:107], v[124:125], off offset:32
	global_load_dwordx4 v[100:103], v[124:125], off offset:16
	global_load_dwordx4 v[96:99], v[124:125], off
	global_load_dwordx4 v[80:83], v[92:93], off
	global_load_dwordx4 v[84:87], v[92:93], off offset:32
	global_load_dwordx4 v[88:91], v[92:93], off offset:64
	s_nop 0
	global_load_dwordx4 v[92:95], v[92:93], off offset:96
	s_branch .LBB0_176

; #define LAS __attribute__((address_space(3)))
; __device__ __forceinline__ unsigned cvtpk(float lo, float hi) { f32x2_t v = {lo, hi}; bf16x2_t b = __builtin_convertvector(v, bf16x2_t); return __builtin_bit_cast(unsigned, b); }
; #define SB_MFMA(a, b, c) __builtin_amdgcn_mfma_f32_32x32x16_bf16((a), (b), (c), 0, 0, 0)
; __device__ __forceinline__ void sw_attn(const bf16* QKV, const float* rope, const float* qg, const float* kg, const float* sinks, bf16* O, LAS unsigned char* lds, int tid) {
;     ...
;                 for (int i = 0; i < 8; ++i) { float lo_, up_; const float own = qv[0][i]; halves(own, lo_, up_); const float oth = hi ? lo_ : up_, c = i < 4 ? rraw[0][i & 3] : rraw[1][i & 3], sn = i < 4 ? rraw[2][i & 3] : rraw[3][i & 3]; qv[0][i] = own * c + oth * (hi ? sn : -sn); }
; #pragma unroll
;                 for (int ks = 0; ks < 4; ++ks) { const v4u w = {cvtpk(qv[ks][0] * QS, qv[ks][1] * QS), cvtpk(qv[ks][2] * QS, qv[ks][3] * QS), cvtpk(qv[ks][4] * QS, qv[ks][5] * QS), cvtpk(qv[ks][6] * QS, qv[ks][7] * QS)}; qf[ks] = __builtin_bit_cast(bf16x8, w); }
;             }
;             if (p < 3) SW_LOADQ(p + 1);
;             const float sink = sinks[hq] * 1.4426950408889634f;
;             f32x16 s[5]; float mx = sink;
;             const float NEG = -__builtin_inff();
; #pragma unroll
;             for (int js = 0; js < 5; ++js) {
; #pragma unroll
;                 for (int r = 0; r < 16; ++r) s[js][r] = 0.f;
;                 const bool live = !(blk == 0 && tb + js < 4);
;                 if (live) {
; #pragma unroll
;                     for (int ks = 0; ks < 4; ++ks) { const bf16x8 a = *(const LAS bf16x8*)(kl + (32 * (tb + js) + l32) * KROW + 32 * ks + 16 * hi); s[js] = SB_MFMA(a, qf[ks], s[js]); }
; #pragma unroll
;                     for (int r = 0; r < 16; ++r) {
;                         const int kk = (r & 3) + 8 * (r >> 2) + 4 * hi;
;                         float v = s[js][r];
;                         if (js == 0) v = (kk > l32) ? v : NEG;
;                         if (js == 4) v = (kk <= l32) ? v : NEG;
;                         s[js][r] = v; mx = fmaxf(mx, v);
.LBB0_176:
	v_mov_b32_e32 v69, v68
	v_pk_mul_f32 v[46:47], v[68:69], v[46:47]
	v_cndmask_b32_e64 v9, v9, -v9, s[40:41]
	s_waitcnt lgkmcnt(1)
	v_pk_mul_f32 v[46:47], v[46:47], v[20:21]
	v_pk_mul_f32 v[20:21], v[68:69], v[44:45]
	v_cndmask_b32_e64 v8, v8, -v8, s[40:41]
	v_pk_mul_f32 v[22:23], v[20:21], v[22:23]
	v_pk_mul_f32 v[20:21], v[68:69], v[42:43]
	v_cndmask_b32_e64 v11, v11, -v11, s[40:41]
	s_waitcnt lgkmcnt(0)
	v_pk_mul_f32 v[16:17], v[20:21], v[16:17]
	v_pk_mul_f32 v[20:21], v[68:69], v[40:41]
	v_cndmask_b32_e64 v10, v10, -v10, s[40:41]
	v_pk_mul_f32 v[44:45], v[20:21], v[18:19]
	v_cndmask_b32_e64 v19, v78, v76, s[40:41]
	v_cndmask_b32_e64 v18, v75, v74, s[40:41]
	v_pk_mul_f32 v[8:9], v[8:9], v[18:19]
	v_cndmask_b32_e64 v13, v13, -v13, s[40:41]
	v_pk_fma_f32 v[4:5], v[4:5], v[70:71], v[8:9]
	v_cndmask_b32_e64 v9, v145, v123, s[40:41]
	v_cndmask_b32_e64 v8, v79, v77, s[40:41]
	v_pk_mul_f32 v[8:9], v[10:11], v[8:9]
	v_cndmask_b32_e64 v12, v12, -v12, s[40:41]
	v_pk_fma_f32 v[6:7], v[6:7], v[72:73], v[8:9]
	v_cndmask_b32_e64 v9, v149, v147, s[40:41]
	v_cndmask_b32_e64 v8, v146, v144, s[40:41]
	v_pk_mul_f32 v[8:9], v[12:13], v[8:9]
	v_cndmask_b32_e64 v15, v15, -v15, s[40:41]
	v_cndmask_b32_e64 v14, v14, -v14, s[40:41]
	v_pk_fma_f32 v[0:1], v[0:1], v[64:65], v[8:9]
	v_cndmask_b32_e64 v9, v152, v151, s[40:41]
	v_cndmask_b32_e64 v8, v150, v148, s[40:41]
	v_pk_mul_f32 v[8:9], v[14:15], v[8:9]
	v_pk_mul_f32 v[62:63], v[68:69], v[62:63]
	v_pk_fma_f32 v[2:3], v[2:3], v[66:67], v[8:9]
	v_pk_mul_f32 v[0:1], v[0:1], s[74:75] op_sel_hi:[1,0]
	v_pk_mul_f32 v[36:37], v[36:37], v[62:63]
	v_pk_mul_f32 v[60:61], v[68:69], v[60:61]
	v_cvt_pk_bf16_f32 v20, v0, v1
	v_pk_mul_f32 v[0:1], v[2:3], s[74:75] op_sel_hi:[1,0]
	v_pk_mul_f32 v[38:39], v[38:39], v[60:61]
	v_pk_mul_f32 v[58:59], v[68:69], v[58:59]
	v_cvt_pk_bf16_f32 v21, v0, v1
	v_pk_mul_f32 v[0:1], v[36:37], s[74:75] op_sel_hi:[1,0]
	v_pk_mul_f32 v[32:33], v[32:33], v[58:59]
	v_pk_mul_f32 v[56:57], v[68:69], v[56:57]
	v_cvt_pk_bf16_f32 v36, v0, v1
	v_pk_mul_f32 v[0:1], v[38:39], s[74:75] op_sel_hi:[1,0]
	v_pk_mul_f32 v[34:35], v[34:35], v[56:57]
	v_pk_mul_f32 v[54:55], v[68:69], v[54:55]
	v_cvt_pk_bf16_f32 v37, v0, v1
	v_pk_mul_f32 v[0:1], v[32:33], s[74:75] op_sel_hi:[1,0]
	v_pk_mul_f32 v[28:29], v[28:29], v[54:55]
	v_pk_mul_f32 v[52:53], v[68:69], v[52:53]
	v_cvt_pk_bf16_f32 v38, v0, v1
	v_pk_mul_f32 v[0:1], v[34:35], s[74:75] op_sel_hi:[1,0]
	v_pk_mul_f32 v[30:31], v[30:31], v[52:53]
	v_pk_mul_f32 v[50:51], v[68:69], v[50:51]
	v_cvt_pk_bf16_f32 v39, v0, v1
	v_pk_mul_f32 v[0:1], v[28:29], s[74:75] op_sel_hi:[1,0]
	v_pk_mul_f32 v[24:25], v[50:51], v[24:25]
	v_pk_mul_f32 v[48:49], v[68:69], v[48:49]
	v_cvt_pk_bf16_f32 v40, v0, v1
	v_pk_mul_f32 v[0:1], v[30:31], s[74:75] op_sel_hi:[1,0]
	s_ashr_i32 s18, s18, 2
	v_pk_mul_f32 v[26:27], v[48:49], v[26:27]
	v_cvt_pk_bf16_f32 v41, v0, v1
	v_pk_mul_f32 v[0:1], v[24:25], s[74:75] op_sel_hi:[1,0]
	s_add_i32 s18, s18, s30
	v_cvt_pk_bf16_f32 v42, v0, v1
	v_pk_mul_f32 v[0:1], v[26:27], s[74:75] op_sel_hi:[1,0]
	s_ashr_i32 s19, s18, 31
	v_cvt_pk_bf16_f32 v43, v0, v1
	v_pk_mul_f32 v[0:1], v[46:47], s[74:75] op_sel_hi:[1,0]
	s_lshl_b64 s[20:21], s[18:19], 2
	v_cvt_pk_bf16_f32 v32, v0, v1
	v_pk_mul_f32 v[0:1], v[22:23], s[74:75] op_sel_hi:[1,0]
	s_add_u32 s20, s27, s20
	v_cvt_pk_bf16_f32 v33, v0, v1
	v_pk_mul_f32 v[0:1], v[16:17], s[74:75] op_sel_hi:[1,0]
	s_addc_u32 s21, s88, s21
	v_cvt_pk_bf16_f32 v34, v0, v1
	v_pk_mul_f32 v[0:1], v[44:45], s[74:75] op_sel_hi:[1,0]
	v_pk_mul_f32 v[4:5], v[4:5], s[74:75] op_sel_hi:[1,0]
	v_cvt_pk_bf16_f32 v35, v0, v1
	v_cvt_pk_bf16_f32 v18, v4, v5
	v_pk_mul_f32 v[4:5], v[6:7], s[74:75] op_sel_hi:[1,0]
	s_andn2_b64 vcc, exec, s[10:11]
	v_cvt_pk_bf16_f32 v19, v4, v5
	v_mov_b32_e32 v182, 0xff800000
	v_mov_b32_e32 v183, 0xff800000
	v_mov_b32_e32 v178, 0xff800000
	v_mov_b32_e32 v179, 0xff800000
	v_mov_b32_e32 v180, 0xff800000
	v_mov_b32_e32 v181, 0xff800000
	v_mov_b32_e32 v156, 0xff800000
	v_mov_b32_e32 v176, 0xff800000
	v_mov_b32_e32 v177, 0xff800000
	v_mov_b32_e32 v47, 0xff800000
	v_mov_b32_e32 v174, 0xff800000
	v_mov_b32_e32 v175, 0xff800000
	v_mov_b32_e32 v44, 0xff800000
	v_mov_b32_e32 v45, 0xff800000
	v_mov_b32_e32 v46, 0xff800000
	v_mov_b32_e32 v173, 0xff800000
	s_waitcnt vmcnt(8)
	v_mul_f32_e32 v123, 0x3fb8aa3b, v236
	v_mov_b32_e32 v0, 0xff800000
	v_mov_b32_e32 v144, v123
	s_cbranch_vccnz .LBB0_178
	ds_read_b128 v[2:5], v134
	ds_read_b128 v[22:25], v134 offset:32
	s_waitcnt lgkmcnt(1)
	v_mfma_f32_32x32x16_bf16 v[2:17], v[2:5], v[18:21], 0
	s_waitcnt lgkmcnt(0)
	v_mfma_f32_32x32x16_bf16 v[2:17], v[22:25], v[36:39], v[2:17]
	ds_read_b128 v[22:25], v134 offset:64
	s_waitcnt lgkmcnt(0)
	v_mfma_f32_32x32x16_bf16 v[2:17], v[22:25], v[40:43], v[2:17]
	ds_read_b128 v[22:25], v134 offset:96
	s_waitcnt lgkmcnt(0)
	v_mfma_f32_32x32x16_bf16 v[2:17], v[22:25], v[32:35], v[2:17]
	s_nop 11
	v_cndmask_b32_e64 v182, v234, v2, s[42:43]
	v_cndmask_b32_e64 v183, v3, v234, s[44:45]
	v_cndmask_b32_e64 v178, v234, v4, s[46:47]
	v_cndmask_b32_e64 v179, v234, v5, s[48:49]
	v_max3_f32 v1, v123, v182, v183
	v_cndmask_b32_e64 v180, v234, v6, s[50:51]
	v_cndmask_b32_e64 v181, v234, v7, s[52:53]
	v_max3_f32 v1, v1, v178, v179
	v_cndmask_b32_e64 v156, v234, v8, s[54:55]
	v_cndmask_b32_e64 v176, v234, v9, s[56:57]
	v_max3_f32 v1, v1, v180, v181
	v_cndmask_b32_e64 v177, v234, v10, s[58:59]
	v_cndmask_b32_e64 v47, v234, v11, s[60:61]
	v_max3_f32 v1, v1, v156, v176
	v_cndmask_b32_e64 v174, v234, v12, s[62:63]
	v_cndmask_b32_e64 v175, v234, v13, s[64:65]
	v_max3_f32 v1, v1, v177, v47
	v_cndmask_b32_e64 v44, v234, v14, s[66:67]
	v_cndmask_b32_e64 v45, v234, v15, s[68:69]
	v_max3_f32 v1, v1, v174, v175
	v_cndmask_b32_e64 v46, v234, v16, s[70:71]
	v_max3_f32 v1, v1, v44, v45
	v_cndmask_b32_e64 v173, v234, v17, s[72:73]
	v_max3_f32 v144, v1, v46, v173

; __global__ void __launch_bounds__(NTHR, 2) fwd_megakernel(Args a) {
;     extern __shared__ __attribute__((aligned(16))) unsigned char lds[];
	.amdhsa_kernel _Z14fwd_megakernel4Args
		.amdhsa_group_segment_fixed_size 0
		.amdhsa_private_segment_fixed_size 0
		.amdhsa_kernarg_size 376
		.amdhsa_user_sgpr_count 2
		.amdhsa_user_sgpr_dispatch_ptr 0
		.amdhsa_user_sgpr_queue_ptr 0
		.amdhsa_user_sgpr_kernarg_segment_ptr 1
		.amdhsa_user_sgpr_dispatch_id 0
		.amdhsa_user_sgpr_kernarg_preload_length 0
		.amdhsa_user_sgpr_kernarg_preload_offset 0
		.amdhsa_user_sgpr_private_segment_size 0
		.amdhsa_uses_dynamic_stack 0
		.amdhsa_enable_private_segment 0
		.amdhsa_system_sgpr_workgroup_id_x 1
		.amdhsa_system_sgpr_workgroup_id_y 0
		.amdhsa_system_sgpr_workgroup_id_z 0
		.amdhsa_system_sgpr_workgroup_info 0
		.amdhsa_system_vgpr_workitem_id 2
		.amdhsa_next_free_vgpr 255
		.amdhsa_next_free_sgpr 102
		.amdhsa_accum_offset 256
		.amdhsa_reserve_vcc 1
		.amdhsa_float_round_mode_32 0
		.amdhsa_float_round_mode_16_64 0
		.amdhsa_float_denorm_mode_32 3
		.amdhsa_float_denorm_mode_16_64 3
		.amdhsa_dx10_clamp 1
		.amdhsa_ieee_mode 1
		.amdhsa_fp16_overflow 0
		.amdhsa_tg_split 0
		.amdhsa_exception_fp_ieee_invalid_op 0
		.amdhsa_exception_fp_denorm_src 0
		.amdhsa_exception_fp_ieee_div_zero 0
		.amdhsa_exception_fp_ieee_overflow 0
		.amdhsa_exception_fp_ieee_underflow 0
		.amdhsa_exception_fp_ieee_inexact 0
		.amdhsa_exception_int_div_zero 0
	.end_amdhsa_kernel

; __global__ void __launch_bounds__(NTHR, 2) fwd_megakernel(Args a) {
;     extern __shared__ __attribute__((aligned(16))) unsigned char lds[];
amdhsa.kernels:
  - .agpr_count:     0
    .args:
      - .offset:         0
        .size:           120
        .value_kind:     by_value
      - .offset:         120
        .size:           4
        .value_kind:     hidden_block_count_x
      - .offset:         124
        .size:           4
        .value_kind:     hidden_block_count_y
      - .offset:         128
        .size:           4
        .value_kind:     hidden_block_count_z
      - .offset:         132
        .size:           2
        .value_kind:     hidden_group_size_x
      - .offset:         134
        .size:           2
        .value_kind:     hidden_group_size_y
      - .offset:         136
        .size:           2
        .value_kind:     hidden_group_size_z
      - .offset:         138
        .size:           2
        .value_kind:     hidden_remainder_x
      - .offset:         140
        .size:           2
        .value_kind:     hidden_remainder_y
      - .offset:         142
        .size:           2
        .value_kind:     hidden_remainder_z
      - .offset:         160
        .size:           8
        .value_kind:     hidden_global_offset_x
      - .offset:         168
        .size:           8
        .value_kind:     hidden_global_offset_y
      - .offset:         176
        .size:           8
        .value_kind:     hidden_global_offset_z
      - .offset:         184
        .size:           2
        .value_kind:     hidden_grid_dims
      - .offset:         208
        .size:           8
        .value_kind:     hidden_multigrid_sync_arg
      - .offset:         240
        .size:           4
        .value_kind:     hidden_dynamic_lds_size
    .group_segment_fixed_size: 0
    .kernarg_segment_align: 8
    .kernarg_segment_size: 376
    .language:       OpenCL C
    .language_version:
      - 2
      - 0
    .max_flat_workgroup_size: 512
    .name:           _Z14fwd_megakernel4Args
    .private_segment_fixed_size: 0
    .sgpr_count:     108
    .sgpr_spill_count: 130
    .symbol:         _Z14fwd_megakernel4Args.kd
    .uniform_work_group_size: 1
    .uses_dynamic_stack: false
    .vgpr_count:     255
    .vgpr_spill_count: 0
    .wavefront_size: 64
